# next-work prefetch in loop slack: last K-loop iteration of out-proj and MLP-down touches the tile's residual rows (4 dword loads per wave, waits bumped 8->12 under the same predicate) so the epilogue'
# baseline (speedup 1.0000x reference)
; #define PG8_STAGE(bufoff, gbase, voff) do { _Pragma("unroll") for (int _i = 0; _i < 2; ++_i) \
;         __builtin_amdgcn_global_load_lds((const unsigned*)((const char*)(gbase) + (voff)[_i]), (PG8_LAS unsigned*)(lds + (bufoff) + ldsw + _i * 8192), 16, 0, 0); } while (0)
; #define PG8_LDA(dst, b, h) do { _Pragma("unroll") for (int m = 0; m < 4; ++m) _Pragma("unroll") for (int k = 0; k < 2; ++k) dst[m][k] = *(const PG8_LAS bf16x8*)(lds + PG8_SA(b, h) + aoff + m * 2048 + k * 1024); } while (0)
; #define PG8_LDB(dst, b, h) do { _Pragma("unroll") for (int n = 0; n < 2; ++n) _Pragma("unroll") for (int k = 0; k < 2; ++k) dst[n][k] = *(const PG8_LAS bf16x8*)(lds + PG8_SB(b, h) + boff + n * 2048 + k * 1024); } while (0)
; #define PG8_MMA(ai, bj, At, Bt) do { __builtin_amdgcn_s_setprio(1); _Pragma("unroll") for (int m = 0; m < 4; ++m) _Pragma("unroll") for (int n = 0; n < 2; ++n) _Pragma("unroll") for (int k = 0; k < 2; ++k) \
;         acc[ai][bj][m][n] = __builtin_amdgcn_mfma_f32_16x16x32_bf16(Bt[n][k], At[m][k], acc[ai][bj][m][n], 0, 0, 0); __builtin_amdgcn_s_setprio(0); } while (0)
; #define PG8_WAIT_V(n) asm volatile("s_waitcnt vmcnt(" #n ")" ::: "memory")
; #define PG8_WAIT_L(n) asm volatile("s_waitcnt lgkmcnt(" #n ")" ::: "memory")
; #define PG8_WAIT_V8_UNLESS(flag) asm volatile("s_cmp_lg_i32 %0, 0\n\ts_cbranch_scc1 .Lpg8rx%=\n\ts_waitcnt vmcnt(8)\n.Lpg8rx%=:" :: "s"(__builtin_amdgcn_readfirstlane(flag)) : "scc", "memory")
; #define PG8_BAR __builtin_amdgcn_s_barrier()
;     __device__ __forceinline__ void operator()(const f32x4 (&acc)[2][2][4][2], const Unit& u, int wr, int wc, int fr, int fq) const {
;     ...
;             for (int bj = 0; bj < 2; ++bj) rv[i][bj] = *(const u32x4*)(Rin + (size_t)(row0 + (i >> 2) * HALF + (i & 3) * 16) * DMODEL + col0 + bj * HALF);
; template <class Epi, class Sched, bool ALIGN_EPI = false, bool SP2 = false>
; __device__ __forceinline__ void gemm_phase(PG8_LAS unsigned char* lds, const Gemm g, const Sched& S, const Epi& E) {
;     ...
;             PG8_WAIT_V8_UNLESS(rx); PG8_WAIT_L(0); PG8_BAR; PG8_MMA(1, 0, At, B0); PG8_MMA(1, 1, At, B1); PG8_BAR; PG8_SCHED;
;             PG8_STAGE(PG8_SA(0, 1), a2 + hstep, voffA); PG8_SCHED; PG8_LDB(B0, 1, 0); PG8_LDB(B1, 1, 1); PG8_SCHED; PG8_LDA(At, 1, 0);
;             PG8_WAIT_V(8); PG8_WAIT_L(0); PG8_BAR; PG8_MMA(0, 0, At, B0); PG8_MMA(0, 1, At, B1); PG8_BAR; PG8_SCHED;
.Lpg8rx3:
	s_waitcnt lgkmcnt(0)
	s_setprio 1
	s_barrier
	v_mfma_f32_16x16x32_bf16 v[60:63], v[120:123], v[164:167], v[60:63]
	v_mfma_f32_16x16x32_bf16 v[56:59], v[132:135], v[164:167], v[56:59]
	v_mfma_f32_16x16x32_bf16 v[44:47], v[120:123], v[172:175], v[44:47]
	v_mfma_f32_16x16x32_bf16 v[40:43], v[132:135], v[172:175], v[40:43]
	v_mfma_f32_16x16x32_bf16 v[28:31], v[120:123], v[180:183], v[28:31]
	v_mfma_f32_16x16x32_bf16 v[24:27], v[132:135], v[180:183], v[24:27]
	v_mfma_f32_16x16x32_bf16 v[12:15], v[120:123], v[188:191], v[12:15]
	v_mfma_f32_16x16x32_bf16 v[8:11], v[132:135], v[188:191], v[8:11]
	v_mfma_f32_16x16x32_bf16 v[60:63], v[128:131], v[168:171], v[60:63]
	v_mfma_f32_16x16x32_bf16 v[56:59], v[136:139], v[168:171], v[56:59]
	v_mfma_f32_16x16x32_bf16 v[44:47], v[128:131], v[176:179], v[44:47]
	v_mfma_f32_16x16x32_bf16 v[40:43], v[136:139], v[176:179], v[40:43]
	v_mfma_f32_16x16x32_bf16 v[28:31], v[128:131], v[184:187], v[28:31]
	v_mfma_f32_16x16x32_bf16 v[24:27], v[136:139], v[184:187], v[24:27]
	v_mfma_f32_16x16x32_bf16 v[12:15], v[128:131], v[214:217], v[12:15]
	v_mfma_f32_16x16x32_bf16 v[8:11], v[136:139], v[214:217], v[8:11]
	v_mfma_f32_16x16x32_bf16 v[52:55], v[140:143], v[164:167], v[52:55]
	v_mfma_f32_16x16x32_bf16 v[48:51], v[156:159], v[164:167], v[48:51]
	v_mfma_f32_16x16x32_bf16 v[36:39], v[140:143], v[172:175], v[36:39]
	v_mfma_f32_16x16x32_bf16 v[32:35], v[156:159], v[172:175], v[32:35]
	v_mfma_f32_16x16x32_bf16 v[20:23], v[140:143], v[180:183], v[20:23]
	v_mfma_f32_16x16x32_bf16 v[16:19], v[156:159], v[180:183], v[16:19]
	v_mfma_f32_16x16x32_bf16 v[4:7], v[140:143], v[188:191], v[4:7]
	v_mfma_f32_16x16x32_bf16 v[0:3], v[156:159], v[188:191], v[0:3]
	v_mfma_f32_16x16x32_bf16 v[52:55], v[144:147], v[168:171], v[52:55]
	v_mfma_f32_16x16x32_bf16 v[48:51], v[160:163], v[168:171], v[48:51]
	v_mfma_f32_16x16x32_bf16 v[36:39], v[144:147], v[176:179], v[36:39]
	v_mfma_f32_16x16x32_bf16 v[32:35], v[160:163], v[176:179], v[32:35]
	v_mfma_f32_16x16x32_bf16 v[20:23], v[144:147], v[184:187], v[20:23]
	v_mfma_f32_16x16x32_bf16 v[16:19], v[160:163], v[184:187], v[16:19]
	v_mfma_f32_16x16x32_bf16 v[4:7], v[144:147], v[214:217], v[4:7]
	v_mfma_f32_16x16x32_bf16 v[0:3], v[160:163], v[214:217], v[0:3]
	s_setprio 0
	s_barrier
	s_mov_b64 s[98:99], s[30:31]
	s_add_u32 s100, s30, 0x40000
	s_addc_u32 s101, s31, 0
	s_add_i32 s30, 0, 0x18000
	s_add_i32 s31, 0, 0x1c000
	v_add_u32_e32 v136, s30, v247
	v_add_u32_e32 v160, s31, v247
	ds_read_b128 v[120:123], v136
	ds_read_b128 v[128:131], v136 offset:1024
	ds_read_b128 v[132:135], v136 offset:2048
	ds_read_b128 v[136:139], v136 offset:3072
	ds_read_b128 v[140:143], v160
	ds_read_b128 v[144:147], v160 offset:1024
	ds_read_b128 v[156:159], v160 offset:2048
	ds_read_b128 v[160:163], v160 offset:3072
	ds_read_b128 v[164:167], v248 offset:32768
	ds_read_b128 v[168:171], v248 offset:33792
	ds_read_b128 v[172:175], v248 offset:34816
	ds_read_b128 v[176:179], v248 offset:35840
	ds_read_b128 v[180:183], v248 offset:36864
	ds_read_b128 v[184:187], v248 offset:37888
	ds_read_b128 v[188:191], v248 offset:38912
	ds_read_b128 v[214:217], v248 offset:39936
	s_cmpk_eq_i32 s62, 0x700
	s_cbranch_scc0 .Lpf514_skip
	v_lshrrev_b32_e32 v118, 1, v192
	v_lshlrev_b32_e32 v118, 11, v118
	v_and_b32_e32 v119, 1, v192
	v_lshl_or_b32 v118, v119, 8, v118
	v_mov_b32_e32 v119, s40
	v_lshl_add_u32 v118, v119, 19, v118
	v_mov_b32_e32 v119, s26
	v_lshl_add_u32 v118, v119, 9, v118
	global_load_dword v119, v118, s[6:7]
	global_load_dword v119, v118, s[6:7] offset:64
	global_load_dword v119, v118, s[6:7] offset:128
	global_load_dword v119, v118, s[6:7] offset:192
.Lpf514_skip:
	s_mov_b32 m0, s46
	s_nop 0
	global_load_lds_dwordx4 v204, s[100:101]
	s_mov_b32 m0, s48
	s_nop 0
	global_load_lds_dwordx4 v206, s[100:101]
	s_cmpk_eq_i32 s62, 0x700
	s_cbranch_scc1 .Lpf514_w3a
	s_waitcnt vmcnt(8)
	s_branch .Lpf514_w3b

; #define PG8_STAGE(bufoff, gbase, voff) do { _Pragma("unroll") for (int _i = 0; _i < 2; ++_i) \
;         __builtin_amdgcn_global_load_lds((const unsigned*)((const char*)(gbase) + (voff)[_i]), (PG8_LAS unsigned*)(lds + (bufoff) + ldsw + _i * 8192), 16, 0, 0); } while (0)
; #define PG8_LDA(dst, b, h) do { _Pragma("unroll") for (int m = 0; m < 4; ++m) _Pragma("unroll") for (int k = 0; k < 2; ++k) dst[m][k] = *(const PG8_LAS bf16x8*)(lds + PG8_SA(b, h) + aoff + m * 2048 + k * 1024); } while (0)
; #define PG8_MMA(ai, bj, At, Bt) do { __builtin_amdgcn_s_setprio(1); _Pragma("unroll") for (int m = 0; m < 4; ++m) _Pragma("unroll") for (int n = 0; n < 2; ++n) _Pragma("unroll") for (int k = 0; k < 2; ++k) \
;         acc[ai][bj][m][n] = __builtin_amdgcn_mfma_f32_16x16x32_bf16(Bt[n][k], At[m][k], acc[ai][bj][m][n], 0, 0, 0); __builtin_amdgcn_s_setprio(0); } while (0)
; #define PG8_WAIT_V(n) asm volatile("s_waitcnt vmcnt(" #n ")" ::: "memory")
; #define PG8_WAIT_L(n) asm volatile("s_waitcnt lgkmcnt(" #n ")" ::: "memory")
; #define PG8_BAR __builtin_amdgcn_s_barrier()
; #define PG8_SCHED __builtin_amdgcn_sched_barrier(0)
; template <class Epi, class Sched, bool ALIGN_EPI = false, bool SP2 = false>
; __device__ __forceinline__ void gemm_phase(PG8_LAS unsigned char* lds, const Gemm g, const Sched& S, const Epi& E) {
;     ...
;             PG8_WAIT_V(8); PG8_WAIT_L(0); PG8_BAR; PG8_MMA(0, 0, At, B0); PG8_MMA(0, 1, At, B1); PG8_BAR; PG8_SCHED;
;             PG8_STAGE(PG8_SB(1, 0), b3, voffB); PG8_STAGE(PG8_SB(1, 1), b3 + hstep, voffB); PG8_STAGE(PG8_SA(1, 0), a3, voffA); PG8_SCHED; PG8_LDA(At, 1, 1);
;             PG8_WAIT_V(8); PG8_WAIT_L(0); PG8_BAR; PG8_MMA(1, 0, At, B0); PG8_MMA(1, 1, At, B1); PG8_BAR; PG8_SCHED;
.Lpf514_w3b:
	s_waitcnt lgkmcnt(0)
	s_setprio 1
	s_barrier
	v_mfma_f32_16x16x32_bf16 v[152:155], v[120:123], v[164:167], v[152:155]
	v_mfma_f32_16x16x32_bf16 v[148:151], v[132:135], v[164:167], v[148:151]
	v_mfma_f32_16x16x32_bf16 v[108:111], v[120:123], v[172:175], v[108:111]
	v_mfma_f32_16x16x32_bf16 v[104:107], v[132:135], v[172:175], v[104:107]
	v_mfma_f32_16x16x32_bf16 v[92:95], v[120:123], v[180:183], v[92:95]
	v_mfma_f32_16x16x32_bf16 v[88:91], v[132:135], v[180:183], v[88:91]
	v_mfma_f32_16x16x32_bf16 v[76:79], v[120:123], v[188:191], v[76:79]
	v_mfma_f32_16x16x32_bf16 v[72:75], v[132:135], v[188:191], v[72:75]
	v_mfma_f32_16x16x32_bf16 v[152:155], v[128:131], v[168:171], v[152:155]
	v_mfma_f32_16x16x32_bf16 v[148:151], v[136:139], v[168:171], v[148:151]
	v_mfma_f32_16x16x32_bf16 v[108:111], v[128:131], v[176:179], v[108:111]
	v_mfma_f32_16x16x32_bf16 v[104:107], v[136:139], v[176:179], v[104:107]
	v_mfma_f32_16x16x32_bf16 v[92:95], v[128:131], v[184:187], v[92:95]
	v_mfma_f32_16x16x32_bf16 v[88:91], v[136:139], v[184:187], v[88:91]
	v_mfma_f32_16x16x32_bf16 v[76:79], v[128:131], v[214:217], v[76:79]
	v_mfma_f32_16x16x32_bf16 v[72:75], v[136:139], v[214:217], v[72:75]
	v_mfma_f32_16x16x32_bf16 v[124:127], v[140:143], v[164:167], v[124:127]
	v_mfma_f32_16x16x32_bf16 v[112:115], v[156:159], v[164:167], v[112:115]
	v_mfma_f32_16x16x32_bf16 v[100:103], v[140:143], v[172:175], v[100:103]
	v_mfma_f32_16x16x32_bf16 v[96:99], v[156:159], v[172:175], v[96:99]
	v_mfma_f32_16x16x32_bf16 v[84:87], v[140:143], v[180:183], v[84:87]
	v_mfma_f32_16x16x32_bf16 v[80:83], v[156:159], v[180:183], v[80:83]
	v_mfma_f32_16x16x32_bf16 v[68:71], v[140:143], v[188:191], v[68:71]
	v_mfma_f32_16x16x32_bf16 v[64:67], v[156:159], v[188:191], v[64:67]
	v_mfma_f32_16x16x32_bf16 v[124:127], v[144:147], v[168:171], v[124:127]
	v_mfma_f32_16x16x32_bf16 v[112:115], v[160:163], v[168:171], v[112:115]
	v_mfma_f32_16x16x32_bf16 v[100:103], v[144:147], v[176:179], v[100:103]
	v_mfma_f32_16x16x32_bf16 v[96:99], v[160:163], v[176:179], v[96:99]
	v_mfma_f32_16x16x32_bf16 v[84:87], v[144:147], v[184:187], v[84:87]
	v_mfma_f32_16x16x32_bf16 v[80:83], v[160:163], v[184:187], v[80:83]
	v_mfma_f32_16x16x32_bf16 v[68:71], v[144:147], v[214:217], v[68:71]
	v_mfma_f32_16x16x32_bf16 v[64:67], v[160:163], v[214:217], v[64:67]
	s_setprio 0
	s_barrier
	ds_read_b128 v[164:167], v248 offset:49152
	ds_read_b128 v[168:171], v248 offset:50176
	ds_read_b128 v[172:175], v248 offset:51200
	ds_read_b128 v[176:179], v248 offset:52224
	ds_read_b128 v[180:183], v248 offset:53248
	ds_read_b128 v[184:187], v248 offset:54272
	ds_read_b128 v[188:191], v248 offset:55296
	ds_read_b128 v[214:217], v248 offset:56320
	s_add_u32 s100, s28, 0x80
	s_addc_u32 s101, s29, 0
	s_add_u32 s28, s28, 0x40080
	s_addc_u32 s29, s29, 0
	s_add_u32 s98, s98, 0x80
	s_addc_u32 s99, s99, 0
	s_add_i32 m0, s30, s39
	s_nop 0
	global_load_lds_dwordx4 v194, s[100:101]
	s_add_i32 m0, m0, 0x2000
	s_nop 0
	global_load_lds_dwordx4 v208, s[100:101]
	s_add_i32 m0, s31, s39
	s_nop 0
	global_load_lds_dwordx4 v194, s[28:29]
	s_add_i32 m0, m0, 0x2000
	s_nop 0
	global_load_lds_dwordx4 v208, s[28:29]
	s_mov_b32 m0, s50
	s_nop 0
	global_load_lds_dwordx4 v204, s[98:99]
	s_mov_b32 m0, s51
	s_nop 0
	global_load_lds_dwordx4 v206, s[98:99]
	s_cmpk_eq_i32 s62, 0x700
	s_cbranch_scc1 .Lpf514_w4a
	s_waitcnt vmcnt(8)
	s_branch .Lpf514_w4b

; #define PG8_MMA(ai, bj, At, Bt) do { __builtin_amdgcn_s_setprio(1); _Pragma("unroll") for (int m = 0; m < 4; ++m) _Pragma("unroll") for (int n = 0; n < 2; ++n) _Pragma("unroll") for (int k = 0; k < 2; ++k) \
;         acc[ai][bj][m][n] = __builtin_amdgcn_mfma_f32_16x16x32_bf16(Bt[n][k], At[m][k], acc[ai][bj][m][n], 0, 0, 0); __builtin_amdgcn_s_setprio(0); } while (0)
; #define PG8_WAIT_V(n) asm volatile("s_waitcnt vmcnt(" #n ")" ::: "memory")
; #define PG8_WAIT_L(n) asm volatile("s_waitcnt lgkmcnt(" #n ")" ::: "memory")
; #define PG8_BAR __builtin_amdgcn_s_barrier()
; #define PG8_SCHED __builtin_amdgcn_sched_barrier(0)
; template <class Epi, class Sched, bool ALIGN_EPI = false, bool SP2 = false>
; __device__ __forceinline__ void gemm_phase(PG8_LAS unsigned char* lds, const Gemm g, const Sched& S, const Epi& E) {
;     ...
;         for (int t = 0; t < nt; t += 2) {
;     ...
;             PG8_WAIT_V(8); PG8_WAIT_L(0); PG8_BAR; PG8_MMA(1, 0, At, B0); PG8_MMA(1, 1, At, B1); PG8_BAR; PG8_SCHED;
.Lpf514_w4b:
	s_waitcnt lgkmcnt(0)
	s_setprio 1
	s_barrier
	v_mfma_f32_16x16x32_bf16 v[60:63], v[120:123], v[164:167], v[60:63]
	v_mfma_f32_16x16x32_bf16 v[56:59], v[132:135], v[164:167], v[56:59]
	v_mfma_f32_16x16x32_bf16 v[44:47], v[120:123], v[172:175], v[44:47]
	v_mfma_f32_16x16x32_bf16 v[40:43], v[132:135], v[172:175], v[40:43]
	v_mfma_f32_16x16x32_bf16 v[28:31], v[120:123], v[180:183], v[28:31]
	v_mfma_f32_16x16x32_bf16 v[24:27], v[132:135], v[180:183], v[24:27]
	v_mfma_f32_16x16x32_bf16 v[12:15], v[120:123], v[188:191], v[12:15]
	v_mfma_f32_16x16x32_bf16 v[8:11], v[132:135], v[188:191], v[8:11]
	v_mfma_f32_16x16x32_bf16 v[60:63], v[128:131], v[168:171], v[60:63]
	v_mfma_f32_16x16x32_bf16 v[56:59], v[136:139], v[168:171], v[56:59]
	v_mfma_f32_16x16x32_bf16 v[44:47], v[128:131], v[176:179], v[44:47]
	v_mfma_f32_16x16x32_bf16 v[40:43], v[136:139], v[176:179], v[40:43]
	v_mfma_f32_16x16x32_bf16 v[28:31], v[128:131], v[184:187], v[28:31]
	v_mfma_f32_16x16x32_bf16 v[24:27], v[136:139], v[184:187], v[24:27]
	v_mfma_f32_16x16x32_bf16 v[12:15], v[128:131], v[214:217], v[12:15]
	v_mfma_f32_16x16x32_bf16 v[8:11], v[136:139], v[214:217], v[8:11]
	v_mfma_f32_16x16x32_bf16 v[52:55], v[140:143], v[164:167], v[52:55]
	v_mfma_f32_16x16x32_bf16 v[48:51], v[156:159], v[164:167], v[48:51]
	v_mfma_f32_16x16x32_bf16 v[36:39], v[140:143], v[172:175], v[36:39]
	v_mfma_f32_16x16x32_bf16 v[32:35], v[156:159], v[172:175], v[32:35]
	v_mfma_f32_16x16x32_bf16 v[20:23], v[140:143], v[180:183], v[20:23]
	v_mfma_f32_16x16x32_bf16 v[16:19], v[156:159], v[180:183], v[16:19]
	v_mfma_f32_16x16x32_bf16 v[4:7], v[140:143], v[188:191], v[4:7]
	v_mfma_f32_16x16x32_bf16 v[0:3], v[156:159], v[188:191], v[0:3]
	v_mfma_f32_16x16x32_bf16 v[52:55], v[144:147], v[168:171], v[52:55]
	v_mfma_f32_16x16x32_bf16 v[48:51], v[160:163], v[168:171], v[48:51]
	v_mfma_f32_16x16x32_bf16 v[36:39], v[144:147], v[176:179], v[36:39]
	v_mfma_f32_16x16x32_bf16 v[32:35], v[160:163], v[176:179], v[32:35]
	v_mfma_f32_16x16x32_bf16 v[20:23], v[144:147], v[184:187], v[20:23]
	v_mfma_f32_16x16x32_bf16 v[16:19], v[160:163], v[184:187], v[16:19]
	v_mfma_f32_16x16x32_bf16 v[4:7], v[144:147], v[214:217], v[4:7]
	v_mfma_f32_16x16x32_bf16 v[0:3], v[160:163], v[214:217], v[0:3]
	s_setprio 0
	s_barrier
	s_add_i32 s58, s58, 2
	s_add_u32 s62, s62, 0x100
	s_addc_u32 s63, s63, 0
	s_cmp_gt_u32 s58, 13
	s_cbranch_scc0 .LBB0_514
	s_and_b64 vcc, exec, s[14:15]
	s_cbranch_vccz .LBB0_517
	s_barrier

; #define PG8_STAGE(bufoff, gbase, voff) do { _Pragma("unroll") for (int _i = 0; _i < 2; ++_i) \
;         __builtin_amdgcn_global_load_lds((const unsigned*)((const char*)(gbase) + (voff)[_i]), (PG8_LAS unsigned*)(lds + (bufoff) + ldsw + _i * 8192), 16, 0, 0); } while (0)
; #define PG8_LDA(dst, b, h) do { _Pragma("unroll") for (int m = 0; m < 4; ++m) _Pragma("unroll") for (int k = 0; k < 2; ++k) dst[m][k] = *(const PG8_LAS bf16x8*)(lds + PG8_SA(b, h) + aoff + m * 2048 + k * 1024); } while (0)
; #define PG8_LDB(dst, b, h) do { _Pragma("unroll") for (int n = 0; n < 2; ++n) _Pragma("unroll") for (int k = 0; k < 2; ++k) dst[n][k] = *(const PG8_LAS bf16x8*)(lds + PG8_SB(b, h) + boff + n * 2048 + k * 1024); } while (0)
; #define PG8_MMA(ai, bj, At, Bt) do { __builtin_amdgcn_s_setprio(1); _Pragma("unroll") for (int m = 0; m < 4; ++m) _Pragma("unroll") for (int n = 0; n < 2; ++n) _Pragma("unroll") for (int k = 0; k < 2; ++k) \
;         acc[ai][bj][m][n] = __builtin_amdgcn_mfma_f32_16x16x32_bf16(Bt[n][k], At[m][k], acc[ai][bj][m][n], 0, 0, 0); __builtin_amdgcn_s_setprio(0); } while (0)
; #define PG8_WAIT_V(n) asm volatile("s_waitcnt vmcnt(" #n ")" ::: "memory")
; #define PG8_WAIT_L(n) asm volatile("s_waitcnt lgkmcnt(" #n ")" ::: "memory")
; #define PG8_WAIT_V8_UNLESS(flag) asm volatile("s_cmp_lg_i32 %0, 0\n\ts_cbranch_scc1 .Lpg8rx%=\n\ts_waitcnt vmcnt(8)\n.Lpg8rx%=:" :: "s"(__builtin_amdgcn_readfirstlane(flag)) : "scc", "memory")
; #define PG8_BAR __builtin_amdgcn_s_barrier()
;     __device__ __forceinline__ void operator()(const f32x4 (&acc)[2][2][4][2], const Unit& u, int wr, int wc, int fr, int fq) const {
;     ...
;             for (int bj = 0; bj < 2; ++bj) rv[i][bj] = *(const u32x4*)(Rin + (size_t)(row0 + (i >> 2) * HALF + (i & 3) * 16) * DMODEL + col0 + bj * HALF);
; template <class Epi, class Sched, bool ALIGN_EPI = false, bool SP2 = false>
; __device__ __forceinline__ void gemm_phase(PG8_LAS unsigned char* lds, const Gemm g, const Sched& S, const Epi& E) {
;     ...
;             PG8_WAIT_V8_UNLESS(rx); PG8_WAIT_L(0); PG8_BAR; PG8_MMA(1, 0, At, B0); PG8_MMA(1, 1, At, B1); PG8_BAR; PG8_SCHED;
;             PG8_STAGE(PG8_SA(0, 1), a2 + hstep, voffA); PG8_SCHED; PG8_LDB(B0, 1, 0); PG8_LDB(B1, 1, 1); PG8_SCHED; PG8_LDA(At, 1, 0);
;             PG8_WAIT_V(8); PG8_WAIT_L(0); PG8_BAR; PG8_MMA(0, 0, At, B0); PG8_MMA(0, 1, At, B1); PG8_BAR; PG8_SCHED;
.Lpg8rx7:
	s_waitcnt lgkmcnt(0)
	s_setprio 1
	s_barrier
	v_mfma_f32_16x16x32_bf16 v[60:63], v[120:123], v[164:167], v[60:63]
	v_mfma_f32_16x16x32_bf16 v[56:59], v[132:135], v[164:167], v[56:59]
	v_mfma_f32_16x16x32_bf16 v[44:47], v[120:123], v[172:175], v[44:47]
	v_mfma_f32_16x16x32_bf16 v[40:43], v[132:135], v[172:175], v[40:43]
	v_mfma_f32_16x16x32_bf16 v[28:31], v[120:123], v[180:183], v[28:31]
	v_mfma_f32_16x16x32_bf16 v[24:27], v[132:135], v[180:183], v[24:27]
	v_mfma_f32_16x16x32_bf16 v[12:15], v[120:123], v[188:191], v[12:15]
	v_mfma_f32_16x16x32_bf16 v[8:11], v[132:135], v[188:191], v[8:11]
	v_mfma_f32_16x16x32_bf16 v[60:63], v[128:131], v[168:171], v[60:63]
	v_mfma_f32_16x16x32_bf16 v[56:59], v[136:139], v[168:171], v[56:59]
	v_mfma_f32_16x16x32_bf16 v[44:47], v[128:131], v[176:179], v[44:47]
	v_mfma_f32_16x16x32_bf16 v[40:43], v[136:139], v[176:179], v[40:43]
	v_mfma_f32_16x16x32_bf16 v[28:31], v[128:131], v[184:187], v[28:31]
	v_mfma_f32_16x16x32_bf16 v[24:27], v[136:139], v[184:187], v[24:27]
	v_mfma_f32_16x16x32_bf16 v[12:15], v[128:131], v[214:217], v[12:15]
	v_mfma_f32_16x16x32_bf16 v[8:11], v[136:139], v[214:217], v[8:11]
	v_mfma_f32_16x16x32_bf16 v[52:55], v[140:143], v[164:167], v[52:55]
	v_mfma_f32_16x16x32_bf16 v[48:51], v[156:159], v[164:167], v[48:51]
	v_mfma_f32_16x16x32_bf16 v[36:39], v[140:143], v[172:175], v[36:39]
	v_mfma_f32_16x16x32_bf16 v[32:35], v[156:159], v[172:175], v[32:35]
	v_mfma_f32_16x16x32_bf16 v[20:23], v[140:143], v[180:183], v[20:23]
	v_mfma_f32_16x16x32_bf16 v[16:19], v[156:159], v[180:183], v[16:19]
	v_mfma_f32_16x16x32_bf16 v[4:7], v[140:143], v[188:191], v[4:7]
	v_mfma_f32_16x16x32_bf16 v[0:3], v[156:159], v[188:191], v[0:3]
	v_mfma_f32_16x16x32_bf16 v[52:55], v[144:147], v[168:171], v[52:55]
	v_mfma_f32_16x16x32_bf16 v[48:51], v[160:163], v[168:171], v[48:51]
	v_mfma_f32_16x16x32_bf16 v[36:39], v[144:147], v[176:179], v[36:39]
	v_mfma_f32_16x16x32_bf16 v[32:35], v[160:163], v[176:179], v[32:35]
	v_mfma_f32_16x16x32_bf16 v[20:23], v[144:147], v[184:187], v[20:23]
	v_mfma_f32_16x16x32_bf16 v[16:19], v[160:163], v[184:187], v[16:19]
	v_mfma_f32_16x16x32_bf16 v[4:7], v[144:147], v[214:217], v[4:7]
	v_mfma_f32_16x16x32_bf16 v[0:3], v[160:163], v[214:217], v[0:3]
	s_setprio 0
	s_barrier
	s_mov_b64 s[98:99], s[30:31]
	s_add_u32 s100, s30, 0x100000
	s_addc_u32 s101, s31, 0
	s_add_i32 s30, 0, 0x18000
	s_add_i32 s31, 0, 0x1c000
	v_add_u32_e32 v136, s30, v247
	v_add_u32_e32 v160, s31, v247
	ds_read_b128 v[120:123], v136
	ds_read_b128 v[128:131], v136 offset:1024
	ds_read_b128 v[132:135], v136 offset:2048
	ds_read_b128 v[136:139], v136 offset:3072
	ds_read_b128 v[140:143], v160
	ds_read_b128 v[144:147], v160 offset:1024
	ds_read_b128 v[156:159], v160 offset:2048
	ds_read_b128 v[160:163], v160 offset:3072
	ds_read_b128 v[164:167], v248 offset:32768
	ds_read_b128 v[168:171], v248 offset:33792
	ds_read_b128 v[172:175], v248 offset:34816
	ds_read_b128 v[176:179], v248 offset:35840
	ds_read_b128 v[180:183], v248 offset:36864
	ds_read_b128 v[184:187], v248 offset:37888
	ds_read_b128 v[188:191], v248 offset:38912
	ds_read_b128 v[214:217], v248 offset:39936
	s_cmpk_eq_i32 s40, 0x1f00
	s_cbranch_scc0 .Lpf965_skip
	v_lshrrev_b32_e32 v118, 1, v192
	v_lshlrev_b32_e32 v118, 11, v118
	v_and_b32_e32 v119, 1, v192
	v_lshl_or_b32 v118, v119, 8, v118
	v_mov_b32_e32 v119, s24
	v_lshl_add_u32 v118, v119, 19, v118
	v_mov_b32_e32 v119, s22
	v_lshl_add_u32 v118, v119, 9, v118
	global_load_dword v119, v118, s[6:7]
	global_load_dword v119, v118, s[6:7] offset:64
	global_load_dword v119, v118, s[6:7] offset:128
	global_load_dword v119, v118, s[6:7] offset:192
.Lpf965_skip:
	s_mov_b32 m0, s43
	s_nop 0
	global_load_lds_dwordx4 v204, s[100:101]
	s_mov_b32 m0, s44
	s_nop 0
	global_load_lds_dwordx4 v206, s[100:101]
	s_cmpk_eq_i32 s40, 0x1f00
	s_cbranch_scc1 .Lpf965_w3a
	s_waitcnt vmcnt(8)
	s_branch .Lpf965_w3b

; #define PG8_STAGE(bufoff, gbase, voff) do { _Pragma("unroll") for (int _i = 0; _i < 2; ++_i) \
;         __builtin_amdgcn_global_load_lds((const unsigned*)((const char*)(gbase) + (voff)[_i]), (PG8_LAS unsigned*)(lds + (bufoff) + ldsw + _i * 8192), 16, 0, 0); } while (0)
; #define PG8_LDA(dst, b, h) do { _Pragma("unroll") for (int m = 0; m < 4; ++m) _Pragma("unroll") for (int k = 0; k < 2; ++k) dst[m][k] = *(const PG8_LAS bf16x8*)(lds + PG8_SA(b, h) + aoff + m * 2048 + k * 1024); } while (0)
; #define PG8_MMA(ai, bj, At, Bt) do { __builtin_amdgcn_s_setprio(1); _Pragma("unroll") for (int m = 0; m < 4; ++m) _Pragma("unroll") for (int n = 0; n < 2; ++n) _Pragma("unroll") for (int k = 0; k < 2; ++k) \
;         acc[ai][bj][m][n] = __builtin_amdgcn_mfma_f32_16x16x32_bf16(Bt[n][k], At[m][k], acc[ai][bj][m][n], 0, 0, 0); __builtin_amdgcn_s_setprio(0); } while (0)
; #define PG8_WAIT_V(n) asm volatile("s_waitcnt vmcnt(" #n ")" ::: "memory")
; #define PG8_WAIT_L(n) asm volatile("s_waitcnt lgkmcnt(" #n ")" ::: "memory")
; #define PG8_BAR __builtin_amdgcn_s_barrier()
; #define PG8_SCHED __builtin_amdgcn_sched_barrier(0)
; template <class Epi, class Sched, bool ALIGN_EPI = false, bool SP2 = false>
; __device__ __forceinline__ void gemm_phase(PG8_LAS unsigned char* lds, const Gemm g, const Sched& S, const Epi& E) {
;     ...
;             PG8_WAIT_V(8); PG8_WAIT_L(0); PG8_BAR; PG8_MMA(0, 0, At, B0); PG8_MMA(0, 1, At, B1); PG8_BAR; PG8_SCHED;
;             PG8_STAGE(PG8_SB(1, 0), b3, voffB); PG8_STAGE(PG8_SB(1, 1), b3 + hstep, voffB); PG8_STAGE(PG8_SA(1, 0), a3, voffA); PG8_SCHED; PG8_LDA(At, 1, 1);
;             PG8_WAIT_V(8); PG8_WAIT_L(0); PG8_BAR; PG8_MMA(1, 0, At, B0); PG8_MMA(1, 1, At, B1); PG8_BAR; PG8_SCHED;
.Lpf965_w3b:
	s_waitcnt lgkmcnt(0)
	s_setprio 1
	s_barrier
	v_mfma_f32_16x16x32_bf16 v[152:155], v[120:123], v[164:167], v[152:155]
	v_mfma_f32_16x16x32_bf16 v[148:151], v[132:135], v[164:167], v[148:151]
	v_mfma_f32_16x16x32_bf16 v[108:111], v[120:123], v[172:175], v[108:111]
	v_mfma_f32_16x16x32_bf16 v[104:107], v[132:135], v[172:175], v[104:107]
	v_mfma_f32_16x16x32_bf16 v[92:95], v[120:123], v[180:183], v[92:95]
	v_mfma_f32_16x16x32_bf16 v[88:91], v[132:135], v[180:183], v[88:91]
	v_mfma_f32_16x16x32_bf16 v[76:79], v[120:123], v[188:191], v[76:79]
	v_mfma_f32_16x16x32_bf16 v[72:75], v[132:135], v[188:191], v[72:75]
	v_mfma_f32_16x16x32_bf16 v[152:155], v[128:131], v[168:171], v[152:155]
	v_mfma_f32_16x16x32_bf16 v[148:151], v[136:139], v[168:171], v[148:151]
	v_mfma_f32_16x16x32_bf16 v[108:111], v[128:131], v[176:179], v[108:111]
	v_mfma_f32_16x16x32_bf16 v[104:107], v[136:139], v[176:179], v[104:107]
	v_mfma_f32_16x16x32_bf16 v[92:95], v[128:131], v[184:187], v[92:95]
	v_mfma_f32_16x16x32_bf16 v[88:91], v[136:139], v[184:187], v[88:91]
	v_mfma_f32_16x16x32_bf16 v[76:79], v[128:131], v[214:217], v[76:79]
	v_mfma_f32_16x16x32_bf16 v[72:75], v[136:139], v[214:217], v[72:75]
	v_mfma_f32_16x16x32_bf16 v[124:127], v[140:143], v[164:167], v[124:127]
	v_mfma_f32_16x16x32_bf16 v[112:115], v[156:159], v[164:167], v[112:115]
	v_mfma_f32_16x16x32_bf16 v[100:103], v[140:143], v[172:175], v[100:103]
	v_mfma_f32_16x16x32_bf16 v[96:99], v[156:159], v[172:175], v[96:99]
	v_mfma_f32_16x16x32_bf16 v[84:87], v[140:143], v[180:183], v[84:87]
	v_mfma_f32_16x16x32_bf16 v[80:83], v[156:159], v[180:183], v[80:83]
	v_mfma_f32_16x16x32_bf16 v[68:71], v[140:143], v[188:191], v[68:71]
	v_mfma_f32_16x16x32_bf16 v[64:67], v[156:159], v[188:191], v[64:67]
	v_mfma_f32_16x16x32_bf16 v[124:127], v[144:147], v[168:171], v[124:127]
	v_mfma_f32_16x16x32_bf16 v[112:115], v[160:163], v[168:171], v[112:115]
	v_mfma_f32_16x16x32_bf16 v[100:103], v[144:147], v[176:179], v[100:103]
	v_mfma_f32_16x16x32_bf16 v[96:99], v[160:163], v[176:179], v[96:99]
	v_mfma_f32_16x16x32_bf16 v[84:87], v[144:147], v[184:187], v[84:87]
	v_mfma_f32_16x16x32_bf16 v[80:83], v[160:163], v[184:187], v[80:83]
	v_mfma_f32_16x16x32_bf16 v[68:71], v[144:147], v[214:217], v[68:71]
	v_mfma_f32_16x16x32_bf16 v[64:67], v[160:163], v[214:217], v[64:67]
	s_setprio 0
	s_barrier
	ds_read_b128 v[164:167], v248 offset:49152
	ds_read_b128 v[168:171], v248 offset:50176
	ds_read_b128 v[172:175], v248 offset:51200
	ds_read_b128 v[176:179], v248 offset:52224
	ds_read_b128 v[180:183], v248 offset:53248
	ds_read_b128 v[184:187], v248 offset:54272
	ds_read_b128 v[188:191], v248 offset:55296
	ds_read_b128 v[214:217], v248 offset:56320
	s_add_u32 s100, s28, 0x80
	s_addc_u32 s101, s29, 0
	s_add_u32 s28, s28, 0x100080
	s_addc_u32 s29, s29, 0
	s_add_u32 s98, s98, 0x80
	s_addc_u32 s99, s99, 0
	s_add_i32 m0, s30, s39
	s_nop 0
	global_load_lds_dwordx4 v194, s[100:101]
	s_add_i32 m0, m0, 0x2000
	s_nop 0
	global_load_lds_dwordx4 v208, s[100:101]
	s_add_i32 m0, s31, s39
	s_nop 0
	global_load_lds_dwordx4 v194, s[28:29]
	s_add_i32 m0, m0, 0x2000
	s_nop 0
	global_load_lds_dwordx4 v208, s[28:29]
	s_mov_b32 m0, s46
	s_nop 0
	global_load_lds_dwordx4 v204, s[98:99]
	s_mov_b32 m0, s48
	s_nop 0
	global_load_lds_dwordx4 v206, s[98:99]
	s_cmpk_eq_i32 s40, 0x1f00
	s_cbranch_scc1 .Lpf965_w4a
	s_waitcnt vmcnt(8)
	s_branch .Lpf965_w4b

; #define PG8_MMA(ai, bj, At, Bt) do { __builtin_amdgcn_s_setprio(1); _Pragma("unroll") for (int m = 0; m < 4; ++m) _Pragma("unroll") for (int n = 0; n < 2; ++n) _Pragma("unroll") for (int k = 0; k < 2; ++k) \
;         acc[ai][bj][m][n] = __builtin_amdgcn_mfma_f32_16x16x32_bf16(Bt[n][k], At[m][k], acc[ai][bj][m][n], 0, 0, 0); __builtin_amdgcn_s_setprio(0); } while (0)
; #define PG8_WAIT_V(n) asm volatile("s_waitcnt vmcnt(" #n ")" ::: "memory")
; #define PG8_WAIT_L(n) asm volatile("s_waitcnt lgkmcnt(" #n ")" ::: "memory")
; #define PG8_BAR __builtin_amdgcn_s_barrier()
; #define PG8_SCHED __builtin_amdgcn_sched_barrier(0)
; template <class Epi, class Sched, bool ALIGN_EPI = false, bool SP2 = false>
; __device__ __forceinline__ void gemm_phase(PG8_LAS unsigned char* lds, const Gemm g, const Sched& S, const Epi& E) {
;     ...
;         for (int t = 0; t < nt; t += 2) {
;     ...
;             PG8_WAIT_V(8); PG8_WAIT_L(0); PG8_BAR; PG8_MMA(1, 0, At, B0); PG8_MMA(1, 1, At, B1); PG8_BAR; PG8_SCHED;
.Lpf965_w4b:
	s_waitcnt lgkmcnt(0)
	s_setprio 1
	s_barrier
	v_mfma_f32_16x16x32_bf16 v[60:63], v[120:123], v[164:167], v[60:63]
	v_mfma_f32_16x16x32_bf16 v[56:59], v[132:135], v[164:167], v[56:59]
	v_mfma_f32_16x16x32_bf16 v[44:47], v[120:123], v[172:175], v[44:47]
	v_mfma_f32_16x16x32_bf16 v[40:43], v[132:135], v[172:175], v[40:43]
	v_mfma_f32_16x16x32_bf16 v[28:31], v[120:123], v[180:183], v[28:31]
	v_mfma_f32_16x16x32_bf16 v[24:27], v[132:135], v[180:183], v[24:27]
	v_mfma_f32_16x16x32_bf16 v[12:15], v[120:123], v[188:191], v[12:15]
	v_mfma_f32_16x16x32_bf16 v[8:11], v[132:135], v[188:191], v[8:11]
	v_mfma_f32_16x16x32_bf16 v[60:63], v[128:131], v[168:171], v[60:63]
	v_mfma_f32_16x16x32_bf16 v[56:59], v[136:139], v[168:171], v[56:59]
	v_mfma_f32_16x16x32_bf16 v[44:47], v[128:131], v[176:179], v[44:47]
	v_mfma_f32_16x16x32_bf16 v[40:43], v[136:139], v[176:179], v[40:43]
	v_mfma_f32_16x16x32_bf16 v[28:31], v[128:131], v[184:187], v[28:31]
	v_mfma_f32_16x16x32_bf16 v[24:27], v[136:139], v[184:187], v[24:27]
	v_mfma_f32_16x16x32_bf16 v[12:15], v[128:131], v[214:217], v[12:15]
	v_mfma_f32_16x16x32_bf16 v[8:11], v[136:139], v[214:217], v[8:11]
	v_mfma_f32_16x16x32_bf16 v[52:55], v[140:143], v[164:167], v[52:55]
	v_mfma_f32_16x16x32_bf16 v[48:51], v[156:159], v[164:167], v[48:51]
	v_mfma_f32_16x16x32_bf16 v[36:39], v[140:143], v[172:175], v[36:39]
	v_mfma_f32_16x16x32_bf16 v[32:35], v[156:159], v[172:175], v[32:35]
	v_mfma_f32_16x16x32_bf16 v[20:23], v[140:143], v[180:183], v[20:23]
	v_mfma_f32_16x16x32_bf16 v[16:19], v[156:159], v[180:183], v[16:19]
	v_mfma_f32_16x16x32_bf16 v[4:7], v[140:143], v[188:191], v[4:7]
	v_mfma_f32_16x16x32_bf16 v[0:3], v[156:159], v[188:191], v[0:3]
	v_mfma_f32_16x16x32_bf16 v[52:55], v[144:147], v[168:171], v[52:55]
	v_mfma_f32_16x16x32_bf16 v[48:51], v[160:163], v[168:171], v[48:51]
	v_mfma_f32_16x16x32_bf16 v[36:39], v[144:147], v[176:179], v[36:39]
	v_mfma_f32_16x16x32_bf16 v[32:35], v[160:163], v[176:179], v[32:35]
	v_mfma_f32_16x16x32_bf16 v[20:23], v[144:147], v[184:187], v[20:23]
	v_mfma_f32_16x16x32_bf16 v[16:19], v[160:163], v[184:187], v[16:19]
	v_mfma_f32_16x16x32_bf16 v[4:7], v[144:147], v[214:217], v[4:7]
	v_mfma_f32_16x16x32_bf16 v[0:3], v[160:163], v[214:217], v[0:3]
	s_setprio 0
	s_barrier
	s_add_i32 s56, s56, 2
	s_add_u32 s40, s40, 0x100
	s_addc_u32 s41, s41, 0
	s_cmp_gt_u32 s56, 61
	s_cbranch_scc0 .LBB0_965
	s_and_b64 vcc, exec, s[10:11]
	s_cbranch_vccz .LBB0_968
	s_barrier
